# FFN_DOWN and SSD_OUT main K-loops rewritten as LDS-DMA double-buffered loops (swizzled linear LDS image, one barrier per k-tile)
# speedup vs baseline: 1.0209x; 1.0150x over previous
; DEVI int TID() { int t = threadIdx.x; asm volatile("" : "+v"(t)); return t; }
;   bf16* As = (bf16*)smem;
;   bf16* Bs = As + 128 * 72;
;   const int tid = TID(), lane = tid & 63, wave = tid >> 6, wm = wave >> 1, wn = wave & 1;
;   f32x16 acc[2][2];
; #pragma unroll
;   for (int i = 0; i < 2; ++i)
; #pragma unroll
;     for (int j = 0; j < 2; ++j) acc[i][j] = zero16();
;   const int lrow = tid >> 3, lkc = (tid & 7) * 8;
;   const bf16* Ag = jb.A + (size_t)max(m0 + lrow, 0) * jb.lda + lkc;
;   const bf16* Ag1 = jb.A + (ptrdiff_t)(m0 + lrow) * jb.lda + lkc;
;   const bf16* Bg = jb.Bt + (size_t)(n0 + lrow) * jb.K + lkc;
;   const size_t astep = (size_t)32 * jb.lda, bstep = (size_t)32 * jb.K;
;   if (kt1 < 0) kt1 = jb.K >> 6;
;   const int nk = kt1 - kt0;
;   Ag += (size_t)kt0 * 64; Ag1 += (size_t)kt0 * 64; Bg += (size_t)kt0 * 64;
;   u32x4 ra0[4], rb0[4], ra1[4], rb1[4];
;     ...
;   bf16* As1 = As + 2 * 128 * 72;
;   bf16* Bs1 = As1 + 128 * 72;
;   G_LOAD(ra0, rb0, 0);
;   if (nk > 1) G_LOAD(ra1, rb1, 1);
;   G_STORE(ra0, rb0, As, Bs);
;   __syncthreads();
.LBB0_2640:
	s_ashr_i32 s2, s12, 31
	s_lshr_b32 s2, s2, 25
	s_add_i32 s2, s12, s2
	s_and_b32 s3, s2, 0xffffff80
	s_sub_i32 s3, s12, s3
	s_ashr_i32 s4, s3, 31
	s_lshr_b32 s4, s4, 28
	s_add_i32 s4, s3, s4
	s_and_b32 s5, s4, 0x1fffff0
	s_sub_i32 s3, s3, s5
	s_lshl_b32 s2, s2, 4
	s_and_b32 s2, s2, 0xfffff800
	s_lshl_b32 s14, s3, 7
	v_mov_b32_e32 v133, v208
	s_add_i32 s14, s14, s2
	s_lshl_b32 s2, s4, 3
	s_waitcnt lgkmcnt(0)
	s_and_b32 s13, s2, 0xffffff80
	s_waitcnt vmcnt(1)
	v_ashrrev_i32_e32 v18, 3, v133
	v_add_u32_e32 v19, s14, v18
	v_max_i32_e32 v20, 0, v19
	v_mov_b64_e32 v[0:1], s[8:9]
	s_movk_i32 s4, 0x1600
	v_lshlrev_b32_e32 v4, 4, v133
	v_add_u32_e32 v21, s13, v18
	v_mad_u64_u32 v[2:3], s[2:3], v20, s4, v[0:1]
	v_and_b32_e32 v4, 0x70, v4
	s_mov_b64 s[96:97], 0x80
	v_lshrrev_b32_e32 v178, 4, v208
	v_and_b32_e32 v178, 7, v178
	v_lshlrev_b32_e32 v178, 4, v178
	v_xor_b32_e32 v4, v4, v178
	v_lshrrev_b32_e32 v179, 6, v208
	v_lshlrev_b32_e32 v179, 10, v179
	v_lshrrev_b32_e32 v180, 5, v208
	v_lshrrev_b32_e32 v181, 1, v208
	v_xor_b32_e32 v180, v180, v181
	v_readfirstlane_b32 s94, v179
	v_and_b32_e32 v180, 1, v180
	v_lshlrev_b32_e32 v180, 4, v180
	v_and_b32_e32 v181, 31, v208
	v_lshlrev_b32_e32 v181, 7, v181
	v_or_b32_e32 v180, v180, v181
	v_lshrrev_b32_e32 v181, 7, v208
	v_lshlrev_b32_e32 v181, 13, v181
	v_or_b32_e32 v194, v180, v181
	v_bfe_u32 v181, v208, 6, 1
	v_lshlrev_b32_e32 v181, 13, v181
	v_or_b32_e32 v195, v180, v181
	v_bfe_u32 v178, v208, 2, 2
	v_xor_b32_e32 v179, 0, v178
	v_lshlrev_b32_e32 v179, 5, v179
	v_or_b32_e32 v170, v194, v179
	v_or_b32_e32 v174, v195, v179
	v_xor_b32_e32 v179, 1, v178
	v_lshlrev_b32_e32 v179, 5, v179
	v_or_b32_e32 v171, v194, v179
	v_or_b32_e32 v175, v195, v179
	v_xor_b32_e32 v179, 2, v178
	v_lshlrev_b32_e32 v179, 5, v179
	v_or_b32_e32 v172, v194, v179
	v_or_b32_e32 v176, v195, v179
	v_xor_b32_e32 v179, 3, v178
	v_lshlrev_b32_e32 v179, 5, v179
	v_or_b32_e32 v173, v194, v179
	v_or_b32_e32 v177, v195, v179
	v_mov_b32_e32 v5, v97
	v_mad_i64_i32 v[0:1], s[2:3], v19, s4, v[0:1]
	v_mad_i64_i32 v[6:7], s[2:3], v21, s4, v[130:131]
	v_lshl_add_u64 v[0:1], v[0:1], 0, v[4:5]
	s_mov_b32 s2, 0x2c000
	v_add_co_u32_e32 v8, vcc, s2, v0
	v_lshl_add_u64 v[6:7], v[6:7], 0, v[4:5]
	s_nop 0
	v_addc_co_u32_e32 v9, vcc, 0, v1, vcc
	v_add_co_u32_e32 v10, vcc, s2, v6
	s_mov_b32 s2, 0x58000
	s_nop 0
	v_addc_co_u32_e32 v11, vcc, 0, v7, vcc
	v_add_co_u32_e32 v12, vcc, s2, v0
	v_lshl_add_u64 v[2:3], v[2:3], 0, v[4:5]
	s_nop 0
	v_addc_co_u32_e32 v13, vcc, 0, v1, vcc
	s_waitcnt vmcnt(0)
	v_add_co_u32_e32 v14, vcc, s2, v6
	s_mov_b32 s2, 0x84000
	s_nop 0
	v_addc_co_u32_e32 v15, vcc, 0, v7, vcc
	v_add_co_u32_e32 v16, vcc, s2, v6
	v_mov_b64_e32 v[64:65], v[2:3]
	v_mov_b64_e32 v[66:67], v[6:7]
	v_addc_co_u32_e32 v17, vcc, 0, v7, vcc
	v_add_co_u32_e32 v0, vcc, s2, v0
	v_mov_b64_e32 v[68:69], v[8:9]
	s_nop 0
	v_addc_co_u32_e32 v1, vcc, 0, v1, vcc
	v_mov_b64_e32 v[70:71], v[10:11]
	v_mov_b64_e32 v[72:73], v[12:13]
	v_mov_b64_e32 v[74:75], v[14:15]
	v_mov_b64_e32 v[78:79], v[16:17]
	v_mov_b64_e32 v[76:77], v[0:1]
	v_ashrrev_i32_e32 v5, 1, v133
	v_lshrrev_b32_e32 v22, 1, v133
	v_and_b32_e32 v151, 0xffffffc0, v5
	v_and_b32_e32 v5, 16, v22
	v_and_b32_e32 v0, 7, v133
	v_and_b32_e32 v150, 0x5f, v133
	v_mad_u64_u32 v[136:137], s[2:3], v18, s91, v[4:5]
	v_and_or_b32 v4, v133, 31, v151
	v_lshlrev_b32_e32 v96, 4, v0
	v_mov_b64_e32 v[0:1], s[6:7]
	v_mul_u32_u24_e32 v22, 0x90, v150
	v_mul_lo_u32 v4, v4, s91
	v_mad_u64_u32 v[138:139], s[2:3], v20, s4, v[0:1]
	v_mad_i64_i32 v[142:143], s[2:3], v19, s4, v[0:1]
	v_mov_b32_e32 v0, 0
	v_add_u32_e32 v137, 0xd800, v136
	v_mad_i64_i32 v[140:141], s[2:3], v21, s4, v[134:135]
	s_mov_b32 s15, -2
	v_add_u32_e32 v152, v5, v4
	v_add_u32_e32 v153, v5, v22
	v_mov_b32_e32 v1, v0
	v_mov_b32_e32 v2, v0
	v_mov_b32_e32 v3, v0
	v_mov_b32_e32 v4, v0
	v_mov_b32_e32 v5, v0
	v_mov_b32_e32 v6, v0
	v_mov_b32_e32 v7, v0
	v_mov_b32_e32 v8, v0
	v_mov_b32_e32 v9, v0
	v_mov_b32_e32 v10, v0
	v_mov_b32_e32 v11, v0
	v_mov_b32_e32 v12, v0
	v_mov_b32_e32 v13, v0
	v_mov_b32_e32 v14, v0
	v_mov_b32_e32 v15, v0
	v_mov_b32_e32 v16, v0
	v_mov_b32_e32 v17, v0
	v_mov_b32_e32 v18, v0
	v_mov_b32_e32 v19, v0
	v_mov_b32_e32 v20, v0
	v_mov_b32_e32 v21, v0
	v_mov_b32_e32 v22, v0
	v_mov_b32_e32 v23, v0
	v_mov_b32_e32 v24, v0
	v_mov_b32_e32 v25, v0
	v_mov_b32_e32 v26, v0
	v_mov_b32_e32 v27, v0
	v_mov_b32_e32 v28, v0
	v_mov_b32_e32 v29, v0
	v_mov_b32_e32 v30, v0
	v_mov_b32_e32 v31, v0
	v_mov_b32_e32 v32, v0
	v_mov_b32_e32 v33, v0
	v_mov_b32_e32 v34, v0
	v_mov_b32_e32 v35, v0
	v_mov_b32_e32 v36, v0
	v_mov_b32_e32 v37, v0
	v_mov_b32_e32 v38, v0
	v_mov_b32_e32 v39, v0
	v_mov_b32_e32 v40, v0
	v_mov_b32_e32 v41, v0
	v_mov_b32_e32 v42, v0
	v_mov_b32_e32 v43, v0
	v_mov_b32_e32 v44, v0
	v_mov_b32_e32 v45, v0
	v_mov_b32_e32 v46, v0
	v_mov_b32_e32 v47, v0
	v_mov_b32_e32 v48, v0
	v_mov_b32_e32 v49, v0
	v_mov_b32_e32 v50, v0
	v_mov_b32_e32 v51, v0
	v_mov_b32_e32 v52, v0
	v_mov_b32_e32 v53, v0
	v_mov_b32_e32 v54, v0
	v_mov_b32_e32 v55, v0
	v_mov_b32_e32 v56, v0
	v_mov_b32_e32 v57, v0
	v_mov_b32_e32 v58, v0
	v_mov_b32_e32 v59, v0
	v_mov_b32_e32 v60, v0
	v_mov_b32_e32 v61, v0
	v_mov_b32_e32 v62, v0
	v_mov_b32_e32 v63, v0
	s_waitcnt lgkmcnt(0)
	s_add_u32 m0, s94, 0x0
	s_nop 0
	global_load_lds_dwordx4 v[64:65], off
	s_add_u32 m0, s94, 0x4000
	s_nop 0
	global_load_lds_dwordx4 v[66:67], off
	s_add_u32 m0, s94, 0x1000
	s_nop 0
	global_load_lds_dwordx4 v[68:69], off
	s_add_u32 m0, s94, 0x5000
	s_nop 0
	global_load_lds_dwordx4 v[70:71], off
	s_add_u32 m0, s94, 0x2000
	s_nop 0
	global_load_lds_dwordx4 v[72:73], off
	s_add_u32 m0, s94, 0x6000
	s_nop 0
	global_load_lds_dwordx4 v[74:75], off
	s_add_u32 m0, s94, 0x3000
	s_nop 0
	global_load_lds_dwordx4 v[76:77], off
	s_add_u32 m0, s94, 0x7000
	s_nop 0
	global_load_lds_dwordx4 v[78:79], off
	s_waitcnt vmcnt(0)
	s_barrier
	s_mov_b32 s15, 0
;     ...
;   for (int kt = 0; kt < nk; kt += 2) {
;     if (kt + 2 < nk) G_LOAD(ra0, rb0, kt + 2);
;     if (kt + 1 < nk) G_STORE(ra1, rb1, As1, Bs1);
;     G_COMPUTE(As, Bs);
;     __syncthreads();
;     if (kt + 1 < nk) {
;       if (kt + 3 < nk) G_LOAD(ra1, rb1, kt + 3);
;       if (kt + 2 < nk) G_STORE(ra0, rb0, As, Bs);
;       G_COMPUTE(As1, Bs1);
;       __syncthreads();
;     }
;   }
.Lmy_dk0:
	ds_read_b128 v[98:101], v170 offset:0
	ds_read_b128 v[106:109], v174 offset:16384
	ds_read_b128 v[102:105], v171 offset:0
	ds_read_b128 v[110:113], v175 offset:16384
	ds_read_b128 v[114:117], v174 offset:20480
	ds_read_b128 v[118:121], v175 offset:20480
	v_lshl_add_u64 v[64:65], v[64:65], 0, s[96:97]
	s_add_u32 m0, s94, 0x8000
	s_nop 0
	global_load_lds_dwordx4 v[64:65], off
	v_lshl_add_u64 v[66:67], v[66:67], 0, s[96:97]
	s_add_u32 m0, s94, 0xc000
	s_nop 0
	global_load_lds_dwordx4 v[66:67], off
	v_lshl_add_u64 v[68:69], v[68:69], 0, s[96:97]
	s_add_u32 m0, s94, 0x9000
	s_nop 0
	global_load_lds_dwordx4 v[68:69], off
	v_lshl_add_u64 v[70:71], v[70:71], 0, s[96:97]
	s_add_u32 m0, s94, 0xd000
	s_nop 0
	global_load_lds_dwordx4 v[70:71], off
	v_lshl_add_u64 v[72:73], v[72:73], 0, s[96:97]
	s_add_u32 m0, s94, 0xa000
	s_nop 0
	global_load_lds_dwordx4 v[72:73], off
	v_lshl_add_u64 v[74:75], v[74:75], 0, s[96:97]
	s_add_u32 m0, s94, 0xe000
	s_nop 0
	global_load_lds_dwordx4 v[74:75], off
	v_lshl_add_u64 v[76:77], v[76:77], 0, s[96:97]
	s_add_u32 m0, s94, 0xb000
	s_nop 0
	global_load_lds_dwordx4 v[76:77], off
	v_lshl_add_u64 v[78:79], v[78:79], 0, s[96:97]
	s_add_u32 m0, s94, 0xf000
	s_nop 0
	global_load_lds_dwordx4 v[78:79], off
	s_waitcnt lgkmcnt(4)
	v_mfma_f32_32x32x16_bf16 v[48:63], v[98:101], v[106:109], v[48:63]
	s_waitcnt lgkmcnt(1)
	v_mfma_f32_32x32x16_bf16 v[32:47], v[98:101], v[114:117], v[32:47]
	ds_read_b128 v[122:125], v170 offset:4096
	ds_read_b128 v[126:129], v171 offset:4096
	s_waitcnt lgkmcnt(1)
	v_mfma_f32_32x32x16_bf16 v[16:31], v[122:125], v[106:109], v[16:31]
	v_mfma_f32_32x32x16_bf16 v[0:15], v[122:125], v[114:117], v[0:15]
	v_mfma_f32_32x32x16_bf16 v[48:63], v[102:105], v[110:113], v[48:63]
	v_mfma_f32_32x32x16_bf16 v[32:47], v[102:105], v[118:121], v[32:47]
	s_waitcnt lgkmcnt(0)
	v_mfma_f32_32x32x16_bf16 v[16:31], v[126:129], v[110:113], v[16:31]
	v_mfma_f32_32x32x16_bf16 v[0:15], v[126:129], v[118:121], v[0:15]
	ds_read_b128 v[98:101], v172 offset:0
	ds_read_b128 v[106:109], v176 offset:16384
	ds_read_b128 v[102:105], v173 offset:0
	ds_read_b128 v[110:113], v177 offset:16384
	ds_read_b128 v[114:117], v176 offset:20480
	ds_read_b128 v[118:121], v177 offset:20480
	s_waitcnt lgkmcnt(4)
	v_mfma_f32_32x32x16_bf16 v[48:63], v[98:101], v[106:109], v[48:63]
	s_waitcnt lgkmcnt(1)
	v_mfma_f32_32x32x16_bf16 v[32:47], v[98:101], v[114:117], v[32:47]
	ds_read_b128 v[122:125], v172 offset:4096
	ds_read_b128 v[126:129], v173 offset:4096
	s_waitcnt lgkmcnt(1)
	v_mfma_f32_32x32x16_bf16 v[16:31], v[122:125], v[106:109], v[16:31]
	v_mfma_f32_32x32x16_bf16 v[0:15], v[122:125], v[114:117], v[0:15]
	v_mfma_f32_32x32x16_bf16 v[48:63], v[102:105], v[110:113], v[48:63]
	v_mfma_f32_32x32x16_bf16 v[32:47], v[102:105], v[118:121], v[32:47]
	s_waitcnt lgkmcnt(0)
	v_mfma_f32_32x32x16_bf16 v[16:31], v[126:129], v[110:113], v[16:31]
	v_mfma_f32_32x32x16_bf16 v[0:15], v[126:129], v[118:121], v[0:15]
	s_waitcnt vmcnt(0)
	s_barrier
	s_add_i32 s15, s15, 2
	s_cmp_ge_u32 s15, 44
	s_cbranch_scc1 .Lmy_dk0_last
	ds_read_b128 v[98:101], v170 offset:32768
	ds_read_b128 v[106:109], v174 offset:49152
	ds_read_b128 v[102:105], v171 offset:32768
	ds_read_b128 v[110:113], v175 offset:49152
	ds_read_b128 v[114:117], v174 offset:53248
	ds_read_b128 v[118:121], v175 offset:53248
	v_lshl_add_u64 v[64:65], v[64:65], 0, s[96:97]
	s_add_u32 m0, s94, 0x0
	s_nop 0
	global_load_lds_dwordx4 v[64:65], off
	v_lshl_add_u64 v[66:67], v[66:67], 0, s[96:97]
	s_add_u32 m0, s94, 0x4000
	s_nop 0
	global_load_lds_dwordx4 v[66:67], off
	v_lshl_add_u64 v[68:69], v[68:69], 0, s[96:97]
	s_add_u32 m0, s94, 0x1000
	s_nop 0
	global_load_lds_dwordx4 v[68:69], off
	v_lshl_add_u64 v[70:71], v[70:71], 0, s[96:97]
	s_add_u32 m0, s94, 0x5000
	s_nop 0
	global_load_lds_dwordx4 v[70:71], off
	v_lshl_add_u64 v[72:73], v[72:73], 0, s[96:97]
	s_add_u32 m0, s94, 0x2000
	s_nop 0
	global_load_lds_dwordx4 v[72:73], off
	v_lshl_add_u64 v[74:75], v[74:75], 0, s[96:97]
	s_add_u32 m0, s94, 0x6000
	s_nop 0
	global_load_lds_dwordx4 v[74:75], off
	v_lshl_add_u64 v[76:77], v[76:77], 0, s[96:97]
	s_add_u32 m0, s94, 0x3000
	s_nop 0
	global_load_lds_dwordx4 v[76:77], off
	v_lshl_add_u64 v[78:79], v[78:79], 0, s[96:97]
	s_add_u32 m0, s94, 0x7000
	s_nop 0
	global_load_lds_dwordx4 v[78:79], off
	s_waitcnt lgkmcnt(4)
	v_mfma_f32_32x32x16_bf16 v[48:63], v[98:101], v[106:109], v[48:63]
	s_waitcnt lgkmcnt(1)
	v_mfma_f32_32x32x16_bf16 v[32:47], v[98:101], v[114:117], v[32:47]
	ds_read_b128 v[122:125], v170 offset:36864
	ds_read_b128 v[126:129], v171 offset:36864
	s_waitcnt lgkmcnt(1)
	v_mfma_f32_32x32x16_bf16 v[16:31], v[122:125], v[106:109], v[16:31]
	v_mfma_f32_32x32x16_bf16 v[0:15], v[122:125], v[114:117], v[0:15]
	v_mfma_f32_32x32x16_bf16 v[48:63], v[102:105], v[110:113], v[48:63]
	v_mfma_f32_32x32x16_bf16 v[32:47], v[102:105], v[118:121], v[32:47]
	s_waitcnt lgkmcnt(0)
	v_mfma_f32_32x32x16_bf16 v[16:31], v[126:129], v[110:113], v[16:31]
	v_mfma_f32_32x32x16_bf16 v[0:15], v[126:129], v[118:121], v[0:15]
	ds_read_b128 v[98:101], v172 offset:32768
	ds_read_b128 v[106:109], v176 offset:49152
	ds_read_b128 v[102:105], v173 offset:32768
	ds_read_b128 v[110:113], v177 offset:49152
	ds_read_b128 v[114:117], v176 offset:53248
	ds_read_b128 v[118:121], v177 offset:53248
	s_waitcnt lgkmcnt(4)
	v_mfma_f32_32x32x16_bf16 v[48:63], v[98:101], v[106:109], v[48:63]
	s_waitcnt lgkmcnt(1)
	v_mfma_f32_32x32x16_bf16 v[32:47], v[98:101], v[114:117], v[32:47]
	ds_read_b128 v[122:125], v172 offset:36864
	ds_read_b128 v[126:129], v173 offset:36864
	s_waitcnt lgkmcnt(1)
	v_mfma_f32_32x32x16_bf16 v[16:31], v[122:125], v[106:109], v[16:31]
	v_mfma_f32_32x32x16_bf16 v[0:15], v[122:125], v[114:117], v[0:15]
	v_mfma_f32_32x32x16_bf16 v[48:63], v[102:105], v[110:113], v[48:63]
	v_mfma_f32_32x32x16_bf16 v[32:47], v[102:105], v[118:121], v[32:47]
	s_waitcnt lgkmcnt(0)
	v_mfma_f32_32x32x16_bf16 v[16:31], v[126:129], v[110:113], v[16:31]
	v_mfma_f32_32x32x16_bf16 v[0:15], v[126:129], v[118:121], v[0:15]
	s_waitcnt vmcnt(0)
	s_barrier
	s_branch .Lmy_dk0
;     ...
;   for (int kt = 0; kt < nk; kt += 2) {
;     if (kt + 2 < nk) G_LOAD(ra0, rb0, kt + 2);
;     if (kt + 1 < nk) G_STORE(ra1, rb1, As1, Bs1);
;     G_COMPUTE(As, Bs);
;     __syncthreads();
;     if (kt + 1 < nk) {
;       if (kt + 3 < nk) G_LOAD(ra1, rb1, kt + 3);
;       if (kt + 2 < nk) G_STORE(ra0, rb0, As, Bs);
;       G_COMPUTE(As1, Bs1);
;       __syncthreads();
;     }
;   }
.Lmy_dk0_last:
	ds_read_b128 v[98:101], v170 offset:32768
	ds_read_b128 v[106:109], v174 offset:49152
	ds_read_b128 v[102:105], v171 offset:32768
	ds_read_b128 v[110:113], v175 offset:49152
	ds_read_b128 v[114:117], v174 offset:53248
	ds_read_b128 v[118:121], v175 offset:53248
	s_waitcnt lgkmcnt(4)
	v_mfma_f32_32x32x16_bf16 v[48:63], v[98:101], v[106:109], v[48:63]
	s_waitcnt lgkmcnt(1)
	v_mfma_f32_32x32x16_bf16 v[32:47], v[98:101], v[114:117], v[32:47]
	ds_read_b128 v[122:125], v170 offset:36864
	ds_read_b128 v[126:129], v171 offset:36864
	s_waitcnt lgkmcnt(1)
	v_mfma_f32_32x32x16_bf16 v[16:31], v[122:125], v[106:109], v[16:31]
	v_mfma_f32_32x32x16_bf16 v[0:15], v[122:125], v[114:117], v[0:15]
	v_mfma_f32_32x32x16_bf16 v[48:63], v[102:105], v[110:113], v[48:63]
	v_mfma_f32_32x32x16_bf16 v[32:47], v[102:105], v[118:121], v[32:47]
	s_waitcnt lgkmcnt(0)
	v_mfma_f32_32x32x16_bf16 v[16:31], v[126:129], v[110:113], v[16:31]
	v_mfma_f32_32x32x16_bf16 v[0:15], v[126:129], v[118:121], v[0:15]
	ds_read_b128 v[98:101], v172 offset:32768
	ds_read_b128 v[106:109], v176 offset:49152
	ds_read_b128 v[102:105], v173 offset:32768
	ds_read_b128 v[110:113], v177 offset:49152
	ds_read_b128 v[114:117], v176 offset:53248
	ds_read_b128 v[118:121], v177 offset:53248
	s_waitcnt lgkmcnt(4)
	v_mfma_f32_32x32x16_bf16 v[48:63], v[98:101], v[106:109], v[48:63]
	s_waitcnt lgkmcnt(1)
	v_mfma_f32_32x32x16_bf16 v[32:47], v[98:101], v[114:117], v[32:47]
	ds_read_b128 v[122:125], v172 offset:36864
	ds_read_b128 v[126:129], v173 offset:36864
	s_waitcnt lgkmcnt(1)
	v_mfma_f32_32x32x16_bf16 v[16:31], v[122:125], v[106:109], v[16:31]
	v_mfma_f32_32x32x16_bf16 v[0:15], v[122:125], v[114:117], v[0:15]
	v_mfma_f32_32x32x16_bf16 v[48:63], v[102:105], v[110:113], v[48:63]
	v_mfma_f32_32x32x16_bf16 v[32:47], v[102:105], v[118:121], v[32:47]
	s_waitcnt lgkmcnt(0)
	v_mfma_f32_32x32x16_bf16 v[16:31], v[126:129], v[110:113], v[16:31]
	v_mfma_f32_32x32x16_bf16 v[0:15], v[126:129], v[118:121], v[0:15]
	s_barrier
	s_branch .LBB0_2648

; DEVI int TID() { int t = threadIdx.x; asm volatile("" : "+v"(t)); return t; }
;   bf16* As = (bf16*)smem;
;   bf16* Bs = As + 128 * 72;
;   const int tid = TID(), lane = tid & 63, wave = tid >> 6, wm = wave >> 1, wn = wave & 1;
;   f32x16 acc[2][2];
; #pragma unroll
;   for (int i = 0; i < 2; ++i)
; #pragma unroll
;     for (int j = 0; j < 2; ++j) acc[i][j] = zero16();
;   const int lrow = tid >> 3, lkc = (tid & 7) * 8;
;   const bf16* Ag = jb.A + (size_t)max(m0 + lrow, 0) * jb.lda + lkc;
;   const bf16* Ag1 = jb.A + (ptrdiff_t)(m0 + lrow) * jb.lda + lkc;
;   const bf16* Bg = jb.Bt + (size_t)(n0 + lrow) * jb.K + lkc;
;   const size_t astep = (size_t)32 * jb.lda, bstep = (size_t)32 * jb.K;
;   if (kt1 < 0) kt1 = jb.K >> 6;
;   const int nk = kt1 - kt0;
;   Ag += (size_t)kt0 * 64; Ag1 += (size_t)kt0 * 64; Bg += (size_t)kt0 * 64;
;   u32x4 ra0[4], rb0[4], ra1[4], rb1[4];
;     ...
;   bf16* As1 = As + 2 * 128 * 72;
;   bf16* Bs1 = As1 + 128 * 72;
;   G_LOAD(ra0, rb0, 0);
;   if (nk > 1) G_LOAD(ra1, rb1, 1);
;   G_STORE(ra0, rb0, As, Bs);
;   __syncthreads();
.LBB0_4100:
	s_ashr_i32 s2, s12, 31
	s_lshr_b32 s2, s2, 25
	s_add_i32 s2, s12, s2
	s_and_b32 s3, s2, 0xffffff80
	s_sub_i32 s3, s12, s3
	s_ashr_i32 s4, s3, 31
	s_lshr_b32 s4, s4, 28
	s_add_i32 s4, s3, s4
	s_and_b32 s5, s4, 0x1fffff0
	s_sub_i32 s3, s3, s5
	s_lshl_b32 s2, s2, 4
	s_and_b32 s2, s2, 0xfffff800
	s_lshl_b32 s14, s3, 7
	v_mov_b32_e32 v133, v208
	s_add_i32 s14, s14, s2
	s_lshl_b32 s2, s4, 3
	v_ashrrev_i32_e32 v22, 3, v133
	v_add_u32_e32 v0, s14, v22
	v_max_i32_e32 v96, 0, v0
	v_lshlrev_b32_e32 v1, 4, v133
	s_waitcnt lgkmcnt(0)
	s_and_b32 s13, s2, 0xffffff80
	v_lshlrev_b64 v[2:3], 12, v[96:97]
	v_and_b32_e32 v96, 0x70, v1
	s_mov_b64 s[96:97], 0x80
	v_lshrrev_b32_e32 v178, 4, v208
	v_and_b32_e32 v178, 7, v178
	v_lshlrev_b32_e32 v178, 4, v178
	v_xor_b32_e32 v96, v96, v178
	v_lshrrev_b32_e32 v179, 6, v208
	v_lshlrev_b32_e32 v179, 10, v179
	v_lshrrev_b32_e32 v180, 5, v208
	v_lshrrev_b32_e32 v181, 1, v208
	v_xor_b32_e32 v180, v180, v181
	v_readfirstlane_b32 s94, v179
	v_and_b32_e32 v180, 1, v180
	v_lshlrev_b32_e32 v180, 4, v180
	v_and_b32_e32 v181, 31, v208
	v_lshlrev_b32_e32 v181, 7, v181
	v_or_b32_e32 v180, v180, v181
	v_lshrrev_b32_e32 v181, 7, v208
	v_lshlrev_b32_e32 v181, 13, v181
	v_or_b32_e32 v194, v180, v181
	v_bfe_u32 v181, v208, 6, 1
	v_lshlrev_b32_e32 v181, 13, v181
	v_or_b32_e32 v195, v180, v181
	v_bfe_u32 v178, v208, 2, 2
	v_xor_b32_e32 v179, 0, v178
	v_lshlrev_b32_e32 v179, 5, v179
	v_or_b32_e32 v170, v194, v179
	v_or_b32_e32 v174, v195, v179
	v_xor_b32_e32 v179, 1, v178
	v_lshlrev_b32_e32 v179, 5, v179
	v_or_b32_e32 v171, v194, v179
	v_or_b32_e32 v175, v195, v179
	v_xor_b32_e32 v179, 2, v178
	v_lshlrev_b32_e32 v179, 5, v179
	v_or_b32_e32 v172, v194, v179
	v_or_b32_e32 v176, v195, v179
	v_xor_b32_e32 v179, 3, v178
	v_lshlrev_b32_e32 v179, 5, v179
	v_or_b32_e32 v173, v194, v179
	v_or_b32_e32 v177, v195, v179
	v_ashrrev_i32_e32 v1, 31, v0
	v_lshlrev_b64 v[0:1], 12, v[0:1]
	v_add_u32_e32 v8, s13, v22
	v_lshl_add_u64 v[6:7], s[8:9], 0, v[0:1]
	v_ashrrev_i32_e32 v9, 31, v8
	v_lshl_add_u64 v[6:7], v[6:7], 0, v[96:97]
	v_lshlrev_b64 v[8:9], 12, v[8:9]
	v_lshl_add_u64 v[10:11], v[130:131], 0, v[8:9]
	v_add_co_u32_e32 v12, vcc, s64, v6
	v_lshl_add_u64 v[10:11], v[10:11], 0, v[96:97]
	s_nop 0
	v_addc_co_u32_e32 v13, vcc, 0, v7, vcc
	s_waitcnt vmcnt(0)
	v_add_co_u32_e32 v14, vcc, s64, v10
	s_mov_b32 s2, 0x40000
	s_nop 0
	v_addc_co_u32_e32 v15, vcc, 0, v11, vcc
	v_add_co_u32_e32 v16, vcc, s2, v6
	v_lshl_add_u64 v[4:5], s[8:9], 0, v[2:3]
	s_nop 0
	v_addc_co_u32_e32 v17, vcc, 0, v7, vcc
	v_add_co_u32_e32 v18, vcc, s2, v10
	s_mov_b32 s2, 0x60000
	s_nop 0
	v_addc_co_u32_e32 v19, vcc, 0, v11, vcc
	v_add_co_u32_e32 v20, vcc, s2, v10
	v_lshl_add_u64 v[4:5], v[4:5], 0, v[96:97]
	s_nop 0
	v_addc_co_u32_e32 v21, vcc, 0, v11, vcc
	v_add_co_u32_e32 v6, vcc, s2, v6
	v_mov_b64_e32 v[64:65], v[4:5]
	v_mov_b64_e32 v[66:67], v[10:11]
	v_addc_co_u32_e32 v7, vcc, 0, v7, vcc
	v_mov_b64_e32 v[68:69], v[12:13]
	v_mov_b64_e32 v[70:71], v[14:15]
	v_mov_b64_e32 v[72:73], v[16:17]
	v_mov_b64_e32 v[74:75], v[18:19]
	v_mov_b64_e32 v[78:79], v[20:21]
	v_mov_b64_e32 v[76:77], v[6:7]
	v_ashrrev_i32_e32 v23, 1, v133
	v_and_b32_e32 v151, 0xffffffc0, v23
	v_lshrrev_b32_e32 v24, 1, v133
	v_and_b32_e32 v150, 0x5f, v133
	v_and_or_b32 v26, v133, 31, v151
	v_and_b32_e32 v25, 7, v133
	v_and_b32_e32 v23, 16, v24
	v_mul_u32_u24_e32 v24, 0x90, v150
	v_mul_lo_u32 v26, v26, s91
	v_mad_u64_u32 v[136:137], s[2:3], v22, s91, v[96:97]
	v_lshl_add_u64 v[142:143], s[6:7], 0, v[0:1]
	v_mov_b32_e32 v0, 0
	v_add_u32_e32 v137, 0xd800, v136
	v_lshlrev_b32_e32 v96, 4, v25
	v_lshl_add_u64 v[138:139], s[6:7], 0, v[2:3]
	v_lshl_add_u64 v[140:141], v[134:135], 0, v[8:9]
	s_mov_b32 s15, -2
	v_add_u32_e32 v152, v23, v26
	v_add_u32_e32 v153, v23, v24
	v_mov_b32_e32 v1, v0
	v_mov_b32_e32 v2, v0
	v_mov_b32_e32 v3, v0
	v_mov_b32_e32 v4, v0
	v_mov_b32_e32 v5, v0
	v_mov_b32_e32 v6, v0
	v_mov_b32_e32 v7, v0
	v_mov_b32_e32 v8, v0
	v_mov_b32_e32 v9, v0
	v_mov_b32_e32 v10, v0
	v_mov_b32_e32 v11, v0
	v_mov_b32_e32 v12, v0
	v_mov_b32_e32 v13, v0
	v_mov_b32_e32 v14, v0
	v_mov_b32_e32 v15, v0
	v_mov_b32_e32 v16, v0
	v_mov_b32_e32 v17, v0
	v_mov_b32_e32 v18, v0
	v_mov_b32_e32 v19, v0
	v_mov_b32_e32 v20, v0
	v_mov_b32_e32 v21, v0
	v_mov_b32_e32 v22, v0
	v_mov_b32_e32 v23, v0
	v_mov_b32_e32 v24, v0
	v_mov_b32_e32 v25, v0
	v_mov_b32_e32 v26, v0
	v_mov_b32_e32 v27, v0
	v_mov_b32_e32 v28, v0
	v_mov_b32_e32 v29, v0
	v_mov_b32_e32 v30, v0
	v_mov_b32_e32 v31, v0
	v_mov_b32_e32 v32, v0
	v_mov_b32_e32 v33, v0
	v_mov_b32_e32 v34, v0
	v_mov_b32_e32 v35, v0
	v_mov_b32_e32 v36, v0
	v_mov_b32_e32 v37, v0
	v_mov_b32_e32 v38, v0
	v_mov_b32_e32 v39, v0
	v_mov_b32_e32 v40, v0
	v_mov_b32_e32 v41, v0
	v_mov_b32_e32 v42, v0
	v_mov_b32_e32 v43, v0
	v_mov_b32_e32 v44, v0
	v_mov_b32_e32 v45, v0
	v_mov_b32_e32 v46, v0
	v_mov_b32_e32 v47, v0
	v_mov_b32_e32 v48, v0
	v_mov_b32_e32 v49, v0
	v_mov_b32_e32 v50, v0
	v_mov_b32_e32 v51, v0
	v_mov_b32_e32 v52, v0
	v_mov_b32_e32 v53, v0
	v_mov_b32_e32 v54, v0
	v_mov_b32_e32 v55, v0
	v_mov_b32_e32 v56, v0
	v_mov_b32_e32 v57, v0
	v_mov_b32_e32 v58, v0
	v_mov_b32_e32 v59, v0
	v_mov_b32_e32 v60, v0
	v_mov_b32_e32 v61, v0
	v_mov_b32_e32 v62, v0
	v_mov_b32_e32 v63, v0
	s_waitcnt lgkmcnt(0)
	s_add_u32 m0, s94, 0x0
	s_nop 0
	global_load_lds_dwordx4 v[64:65], off
	s_add_u32 m0, s94, 0x4000
	s_nop 0
	global_load_lds_dwordx4 v[66:67], off
	s_add_u32 m0, s94, 0x1000
	s_nop 0
	global_load_lds_dwordx4 v[68:69], off
	s_add_u32 m0, s94, 0x5000
	s_nop 0
	global_load_lds_dwordx4 v[70:71], off
	s_add_u32 m0, s94, 0x2000
	s_nop 0
	global_load_lds_dwordx4 v[72:73], off
	s_add_u32 m0, s94, 0x6000
	s_nop 0
	global_load_lds_dwordx4 v[74:75], off
	s_add_u32 m0, s94, 0x3000
	s_nop 0
	global_load_lds_dwordx4 v[76:77], off
	s_add_u32 m0, s94, 0x7000
	s_nop 0
	global_load_lds_dwordx4 v[78:79], off
	s_waitcnt vmcnt(0)
	s_barrier
	s_mov_b32 s15, 0
;     ...
;   for (int kt = 0; kt < nk; kt += 2) {
;     if (kt + 2 < nk) G_LOAD(ra0, rb0, kt + 2);
;     if (kt + 1 < nk) G_STORE(ra1, rb1, As1, Bs1);
;     G_COMPUTE(As, Bs);
;     __syncthreads();
;     if (kt + 1 < nk) {
;       if (kt + 3 < nk) G_LOAD(ra1, rb1, kt + 3);
;       if (kt + 2 < nk) G_STORE(ra0, rb0, As, Bs);
;       G_COMPUTE(As1, Bs1);
;       __syncthreads();
;     }
;   }
.Lmy_dk4100:
	ds_read_b128 v[98:101], v170 offset:0
	ds_read_b128 v[106:109], v174 offset:16384
	ds_read_b128 v[102:105], v171 offset:0
	ds_read_b128 v[110:113], v175 offset:16384
	ds_read_b128 v[114:117], v174 offset:20480
	ds_read_b128 v[118:121], v175 offset:20480
	v_lshl_add_u64 v[64:65], v[64:65], 0, s[96:97]
	s_add_u32 m0, s94, 0x8000
	s_nop 0
	global_load_lds_dwordx4 v[64:65], off
	v_lshl_add_u64 v[66:67], v[66:67], 0, s[96:97]
	s_add_u32 m0, s94, 0xc000
	s_nop 0
	global_load_lds_dwordx4 v[66:67], off
	v_lshl_add_u64 v[68:69], v[68:69], 0, s[96:97]
	s_add_u32 m0, s94, 0x9000
	s_nop 0
	global_load_lds_dwordx4 v[68:69], off
	v_lshl_add_u64 v[70:71], v[70:71], 0, s[96:97]
	s_add_u32 m0, s94, 0xd000
	s_nop 0
	global_load_lds_dwordx4 v[70:71], off
	v_lshl_add_u64 v[72:73], v[72:73], 0, s[96:97]
	s_add_u32 m0, s94, 0xa000
	s_nop 0
	global_load_lds_dwordx4 v[72:73], off
	v_lshl_add_u64 v[74:75], v[74:75], 0, s[96:97]
	s_add_u32 m0, s94, 0xe000
	s_nop 0
	global_load_lds_dwordx4 v[74:75], off
	v_lshl_add_u64 v[76:77], v[76:77], 0, s[96:97]
	s_add_u32 m0, s94, 0xb000
	s_nop 0
	global_load_lds_dwordx4 v[76:77], off
	v_lshl_add_u64 v[78:79], v[78:79], 0, s[96:97]
	s_add_u32 m0, s94, 0xf000
	s_nop 0
	global_load_lds_dwordx4 v[78:79], off
	s_waitcnt lgkmcnt(4)
	v_mfma_f32_32x32x16_bf16 v[48:63], v[98:101], v[106:109], v[48:63]
	s_waitcnt lgkmcnt(1)
	v_mfma_f32_32x32x16_bf16 v[32:47], v[98:101], v[114:117], v[32:47]
	ds_read_b128 v[122:125], v170 offset:4096
	ds_read_b128 v[126:129], v171 offset:4096
	s_waitcnt lgkmcnt(1)
	v_mfma_f32_32x32x16_bf16 v[16:31], v[122:125], v[106:109], v[16:31]
	v_mfma_f32_32x32x16_bf16 v[0:15], v[122:125], v[114:117], v[0:15]
	v_mfma_f32_32x32x16_bf16 v[48:63], v[102:105], v[110:113], v[48:63]
	v_mfma_f32_32x32x16_bf16 v[32:47], v[102:105], v[118:121], v[32:47]
	s_waitcnt lgkmcnt(0)
	v_mfma_f32_32x32x16_bf16 v[16:31], v[126:129], v[110:113], v[16:31]
	v_mfma_f32_32x32x16_bf16 v[0:15], v[126:129], v[118:121], v[0:15]
	ds_read_b128 v[98:101], v172 offset:0
	ds_read_b128 v[106:109], v176 offset:16384
	ds_read_b128 v[102:105], v173 offset:0
	ds_read_b128 v[110:113], v177 offset:16384
	ds_read_b128 v[114:117], v176 offset:20480
	ds_read_b128 v[118:121], v177 offset:20480
	s_waitcnt lgkmcnt(4)
	v_mfma_f32_32x32x16_bf16 v[48:63], v[98:101], v[106:109], v[48:63]
	s_waitcnt lgkmcnt(1)
	v_mfma_f32_32x32x16_bf16 v[32:47], v[98:101], v[114:117], v[32:47]
	ds_read_b128 v[122:125], v172 offset:4096
	ds_read_b128 v[126:129], v173 offset:4096
	s_waitcnt lgkmcnt(1)
	v_mfma_f32_32x32x16_bf16 v[16:31], v[122:125], v[106:109], v[16:31]
	v_mfma_f32_32x32x16_bf16 v[0:15], v[122:125], v[114:117], v[0:15]
	v_mfma_f32_32x32x16_bf16 v[48:63], v[102:105], v[110:113], v[48:63]
	v_mfma_f32_32x32x16_bf16 v[32:47], v[102:105], v[118:121], v[32:47]
	s_waitcnt lgkmcnt(0)
	v_mfma_f32_32x32x16_bf16 v[16:31], v[126:129], v[110:113], v[16:31]
	v_mfma_f32_32x32x16_bf16 v[0:15], v[126:129], v[118:121], v[0:15]
	s_waitcnt vmcnt(0)
	s_barrier
	s_add_i32 s15, s15, 2
	s_cmp_ge_u32 s15, 32
	s_cbranch_scc1 .Lmy_dk4100_last
	ds_read_b128 v[98:101], v170 offset:32768
	ds_read_b128 v[106:109], v174 offset:49152
	ds_read_b128 v[102:105], v171 offset:32768
	ds_read_b128 v[110:113], v175 offset:49152
	ds_read_b128 v[114:117], v174 offset:53248
	ds_read_b128 v[118:121], v175 offset:53248
	v_lshl_add_u64 v[64:65], v[64:65], 0, s[96:97]
	s_add_u32 m0, s94, 0x0
	s_nop 0
	global_load_lds_dwordx4 v[64:65], off
	v_lshl_add_u64 v[66:67], v[66:67], 0, s[96:97]
	s_add_u32 m0, s94, 0x4000
	s_nop 0
	global_load_lds_dwordx4 v[66:67], off
	v_lshl_add_u64 v[68:69], v[68:69], 0, s[96:97]
	s_add_u32 m0, s94, 0x1000
	s_nop 0
	global_load_lds_dwordx4 v[68:69], off
	v_lshl_add_u64 v[70:71], v[70:71], 0, s[96:97]
	s_add_u32 m0, s94, 0x5000
	s_nop 0
	global_load_lds_dwordx4 v[70:71], off
	v_lshl_add_u64 v[72:73], v[72:73], 0, s[96:97]
	s_add_u32 m0, s94, 0x2000
	s_nop 0
	global_load_lds_dwordx4 v[72:73], off
	v_lshl_add_u64 v[74:75], v[74:75], 0, s[96:97]
	s_add_u32 m0, s94, 0x6000
	s_nop 0
	global_load_lds_dwordx4 v[74:75], off
	v_lshl_add_u64 v[76:77], v[76:77], 0, s[96:97]
	s_add_u32 m0, s94, 0x3000
	s_nop 0
	global_load_lds_dwordx4 v[76:77], off
	v_lshl_add_u64 v[78:79], v[78:79], 0, s[96:97]
	s_add_u32 m0, s94, 0x7000
	s_nop 0
	global_load_lds_dwordx4 v[78:79], off
	s_waitcnt lgkmcnt(4)
	v_mfma_f32_32x32x16_bf16 v[48:63], v[98:101], v[106:109], v[48:63]
	s_waitcnt lgkmcnt(1)
	v_mfma_f32_32x32x16_bf16 v[32:47], v[98:101], v[114:117], v[32:47]
	ds_read_b128 v[122:125], v170 offset:36864
	ds_read_b128 v[126:129], v171 offset:36864
	s_waitcnt lgkmcnt(1)
	v_mfma_f32_32x32x16_bf16 v[16:31], v[122:125], v[106:109], v[16:31]
	v_mfma_f32_32x32x16_bf16 v[0:15], v[122:125], v[114:117], v[0:15]
	v_mfma_f32_32x32x16_bf16 v[48:63], v[102:105], v[110:113], v[48:63]
	v_mfma_f32_32x32x16_bf16 v[32:47], v[102:105], v[118:121], v[32:47]
	s_waitcnt lgkmcnt(0)
	v_mfma_f32_32x32x16_bf16 v[16:31], v[126:129], v[110:113], v[16:31]
	v_mfma_f32_32x32x16_bf16 v[0:15], v[126:129], v[118:121], v[0:15]
	ds_read_b128 v[98:101], v172 offset:32768
	ds_read_b128 v[106:109], v176 offset:49152
	ds_read_b128 v[102:105], v173 offset:32768
	ds_read_b128 v[110:113], v177 offset:49152
	ds_read_b128 v[114:117], v176 offset:53248
	ds_read_b128 v[118:121], v177 offset:53248
	s_waitcnt lgkmcnt(4)
	v_mfma_f32_32x32x16_bf16 v[48:63], v[98:101], v[106:109], v[48:63]
	s_waitcnt lgkmcnt(1)
	v_mfma_f32_32x32x16_bf16 v[32:47], v[98:101], v[114:117], v[32:47]
	ds_read_b128 v[122:125], v172 offset:36864
	ds_read_b128 v[126:129], v173 offset:36864
	s_waitcnt lgkmcnt(1)
	v_mfma_f32_32x32x16_bf16 v[16:31], v[122:125], v[106:109], v[16:31]
	v_mfma_f32_32x32x16_bf16 v[0:15], v[122:125], v[114:117], v[0:15]
	v_mfma_f32_32x32x16_bf16 v[48:63], v[102:105], v[110:113], v[48:63]
	v_mfma_f32_32x32x16_bf16 v[32:47], v[102:105], v[118:121], v[32:47]
	s_waitcnt lgkmcnt(0)
	v_mfma_f32_32x32x16_bf16 v[16:31], v[126:129], v[110:113], v[16:31]
	v_mfma_f32_32x32x16_bf16 v[0:15], v[126:129], v[118:121], v[0:15]
	s_waitcnt vmcnt(0)
	s_barrier
	s_branch .Lmy_dk4100
